# v108: v106 plus streaming (nt) residual loads in the residual epilogues
# speedup vs baseline: 1.0029x; 1.0029x over previous
.Lres_nobias:
	s_nop 2
	global_load_dwordx4 v[216:219], v250, s[8:9] offset:0
	global_load_dwordx4 v[220:223], v250, s[8:9] offset:64
	global_load_dwordx4 v[240:243], v250, s[8:9] offset:512
	global_load_dwordx4 v[244:247], v250, s[8:9] offset:576
	v_readlane_b32 s3, v254, 61
	s_mov_b32 s2, -1
	s_cmp_eq_u32 s3, 8
	s_cselect_b32 s2, 2, s2
	s_cmp_eq_u32 s3, 10
	s_cselect_b32 s2, 4, s2
	s_cmp_eq_u32 s3, 17
	s_cselect_b32 s2, 6, s2
	s_cmp_eq_u32 s3, 19
	s_cselect_b32 s2, 8, s2
	s_cmp_eq_u32 s3, 21
	s_cselect_b32 s2, 9, s2
	s_cmp_eq_u32 s3, 25
	s_cselect_b32 s2, 10, s2
	s_cmp_eq_u32 s3, 27
	s_cselect_b32 s2, 12, s2
	s_cmp_eq_u32 s3, 29
	s_cselect_b32 s2, 13, s2
	s_cmp_eq_u32 s3, 32
	s_cselect_b32 s2, 14, s2
	s_cmp_eq_u32 s3, 34
	s_cselect_b32 s2, 99, s2
	s_mov_b32 s100, s2
	s_cmp_lt_i32 s2, 0
	s_cbranch_scc0 .Lrf_fused
	global_load_dwordx4 v[130:133], v248, s[10:11] offset:0 nt
	s_add_u32 s14, s10, 0x10000
	s_addc_u32 s15, s11, 0
	global_load_dwordx4 v[134:137], v248, s[14:15] offset:0 nt
	s_add_u32 s14, s10, 0x20000
	s_addc_u32 s15, s11, 0
	global_load_dwordx4 v[138:141], v248, s[14:15] offset:0 nt
	s_add_u32 s14, s10, 0x30000
	s_addc_u32 s15, s11, 0
	global_load_dwordx4 v[142:145], v248, s[14:15] offset:0 nt
	s_add_u32 s14, s10, 0x80000
	s_addc_u32 s15, s11, 0
	global_load_dwordx4 v[146:149], v248, s[14:15] offset:0 nt
	s_add_u32 s14, s10, 0x90000
	s_addc_u32 s15, s11, 0
	global_load_dwordx4 v[150:153], v248, s[14:15] offset:0 nt
	s_add_u32 s14, s10, 0xa0000
	s_addc_u32 s15, s11, 0
	global_load_dwordx4 v[154:157], v248, s[14:15] offset:0 nt
	s_add_u32 s14, s10, 0xb0000
	s_addc_u32 s15, s11, 0
	global_load_dwordx4 v[158:161], v248, s[14:15] offset:0 nt
	global_load_dwordx4 v[162:165], v248, s[10:11] offset:64 nt
	s_add_u32 s14, s10, 0x10000
	s_addc_u32 s15, s11, 0
	global_load_dwordx4 v[188:191], v248, s[14:15] offset:64 nt
	s_add_u32 s14, s10, 0x20000
	s_addc_u32 s15, s11, 0
	global_load_dwordx4 v[192:195], v248, s[14:15] offset:64 nt
	s_add_u32 s14, s10, 0x30000
	s_addc_u32 s15, s11, 0
	global_load_dwordx4 v[196:199], v248, s[14:15] offset:64 nt
	s_add_u32 s14, s10, 0x80000
	s_addc_u32 s15, s11, 0
	global_load_dwordx4 v[200:203], v248, s[14:15] offset:64 nt
	s_add_u32 s14, s10, 0x90000
	s_addc_u32 s15, s11, 0
	global_load_dwordx4 v[204:207], v248, s[14:15] offset:64 nt
	s_add_u32 s14, s10, 0xa0000
	s_addc_u32 s15, s11, 0
	global_load_dwordx4 v[208:211], v248, s[14:15] offset:64 nt
	s_add_u32 s14, s10, 0xb0000
	s_addc_u32 s15, s11, 0
	global_load_dwordx4 v[212:215], v248, s[14:15] offset:64 nt
	s_waitcnt vmcnt(12)
	v_pk_mul_f32 v[216:217], s[28:29], v[216:217]
	v_pk_mul_f32 v[218:219], s[28:29], v[218:219]
	v_pk_mul_f32 v[220:221], s[28:29], v[220:221]
	v_pk_mul_f32 v[222:223], s[28:29], v[222:223]
	v_pk_mul_f32 v[240:241], s[28:29], v[240:241]
	v_pk_mul_f32 v[242:243], s[28:29], v[242:243]
	v_pk_mul_f32 v[244:245], s[28:29], v[244:245]
	v_pk_mul_f32 v[246:247], s[28:29], v[246:247]
	v_pk_fma_f32 v[130:131], v[216:217], v[126:127], v[130:131]
	v_pk_fma_f32 v[132:133], v[218:219], v[128:129], v[132:133]
	v_pk_fma_f32 v[134:135], v[216:217], v[110:111], v[134:135]
	v_pk_fma_f32 v[136:137], v[218:219], v[112:113], v[136:137]
	v_pk_fma_f32 v[138:139], v[216:217], v[94:95], v[138:139]
	v_pk_fma_f32 v[140:141], v[218:219], v[96:97], v[140:141]
	v_pk_fma_f32 v[142:143], v[216:217], v[78:79], v[142:143]
	v_pk_fma_f32 v[144:145], v[218:219], v[80:81], v[144:145]
	global_store_dwordx4 v248, v[130:133], s[12:13] offset:0
	s_add_u32 s2, s12, 0x10000
	s_addc_u32 s3, s13, 0
	global_store_dwordx4 v248, v[134:137], s[2:3] offset:0
	s_add_u32 s2, s12, 0x20000
	s_addc_u32 s3, s13, 0
	global_store_dwordx4 v248, v[138:141], s[2:3] offset:0
	s_add_u32 s2, s12, 0x30000
	s_addc_u32 s3, s13, 0
	global_store_dwordx4 v248, v[142:145], s[2:3] offset:0
	global_load_dwordx4 v[130:133], v248, s[10:11] offset:512 nt
	s_add_u32 s14, s10, 0x10000
	s_addc_u32 s15, s11, 0
	global_load_dwordx4 v[134:137], v248, s[14:15] offset:512 nt
	s_add_u32 s14, s10, 0x20000
	s_addc_u32 s15, s11, 0
	global_load_dwordx4 v[138:141], v248, s[14:15] offset:512 nt
	s_add_u32 s14, s10, 0x30000
	s_addc_u32 s15, s11, 0
	global_load_dwordx4 v[142:145], v248, s[14:15] offset:512 nt
	s_waitcnt vmcnt(16)
	v_pk_fma_f32 v[146:147], v[216:217], v[62:63], v[146:147]
	v_pk_fma_f32 v[148:149], v[218:219], v[64:65], v[148:149]
	v_pk_fma_f32 v[150:151], v[216:217], v[46:47], v[150:151]
	v_pk_fma_f32 v[152:153], v[218:219], v[48:49], v[152:153]
	v_pk_fma_f32 v[154:155], v[216:217], v[30:31], v[154:155]
	v_pk_fma_f32 v[156:157], v[218:219], v[32:33], v[156:157]
	v_pk_fma_f32 v[158:159], v[216:217], v[14:15], v[158:159]
	v_pk_fma_f32 v[160:161], v[218:219], v[16:17], v[160:161]
	s_add_u32 s2, s12, 0x80000
	s_addc_u32 s3, s13, 0
	global_store_dwordx4 v248, v[146:149], s[2:3] offset:0
	s_add_u32 s2, s12, 0x90000
	s_addc_u32 s3, s13, 0
	global_store_dwordx4 v248, v[150:153], s[2:3] offset:0
	s_add_u32 s2, s12, 0xa0000
	s_addc_u32 s3, s13, 0
	global_store_dwordx4 v248, v[154:157], s[2:3] offset:0
	s_add_u32 s2, s12, 0xb0000
	s_addc_u32 s3, s13, 0
	global_store_dwordx4 v248, v[158:161], s[2:3] offset:0
	s_add_u32 s14, s10, 0x80000
	s_addc_u32 s15, s11, 0
	global_load_dwordx4 v[146:149], v248, s[14:15] offset:512 nt
	s_add_u32 s14, s10, 0x90000
	s_addc_u32 s15, s11, 0
	global_load_dwordx4 v[150:153], v248, s[14:15] offset:512 nt
	s_add_u32 s14, s10, 0xa0000
	s_addc_u32 s15, s11, 0
	global_load_dwordx4 v[154:157], v248, s[14:15] offset:512 nt
	s_add_u32 s14, s10, 0xb0000
	s_addc_u32 s15, s11, 0
	global_load_dwordx4 v[158:161], v248, s[14:15] offset:512 nt
	s_waitcnt vmcnt(20)
	v_pk_fma_f32 v[162:163], v[220:221], v[122:123], v[162:163]
	v_pk_fma_f32 v[164:165], v[222:223], v[124:125], v[164:165]
	v_pk_fma_f32 v[188:189], v[220:221], v[106:107], v[188:189]
	v_pk_fma_f32 v[190:191], v[222:223], v[108:109], v[190:191]
	v_pk_fma_f32 v[192:193], v[220:221], v[90:91], v[192:193]
	v_pk_fma_f32 v[194:195], v[222:223], v[92:93], v[194:195]
	v_pk_fma_f32 v[196:197], v[220:221], v[74:75], v[196:197]
	v_pk_fma_f32 v[198:199], v[222:223], v[76:77], v[198:199]
	global_store_dwordx4 v248, v[162:165], s[12:13] offset:64
	s_add_u32 s2, s12, 0x10000
	s_addc_u32 s3, s13, 0
	global_store_dwordx4 v248, v[188:191], s[2:3] offset:64
	s_add_u32 s2, s12, 0x20000
	s_addc_u32 s3, s13, 0
	global_store_dwordx4 v248, v[192:195], s[2:3] offset:64
	s_add_u32 s2, s12, 0x30000
	s_addc_u32 s3, s13, 0
	global_store_dwordx4 v248, v[196:199], s[2:3] offset:64
	global_load_dwordx4 v[162:165], v248, s[10:11] offset:576 nt
	s_add_u32 s14, s10, 0x10000
	s_addc_u32 s15, s11, 0
	global_load_dwordx4 v[188:191], v248, s[14:15] offset:576 nt
	s_add_u32 s14, s10, 0x20000
	s_addc_u32 s15, s11, 0
	global_load_dwordx4 v[192:195], v248, s[14:15] offset:576 nt
	s_add_u32 s14, s10, 0x30000
	s_addc_u32 s15, s11, 0
	global_load_dwordx4 v[196:199], v248, s[14:15] offset:576 nt
	s_waitcnt vmcnt(24)
	v_pk_fma_f32 v[200:201], v[220:221], v[58:59], v[200:201]
	v_pk_fma_f32 v[202:203], v[222:223], v[60:61], v[202:203]
	v_pk_fma_f32 v[204:205], v[220:221], v[42:43], v[204:205]
	v_pk_fma_f32 v[206:207], v[222:223], v[44:45], v[206:207]
	v_pk_fma_f32 v[208:209], v[220:221], v[26:27], v[208:209]
	v_pk_fma_f32 v[210:211], v[222:223], v[28:29], v[210:211]
	v_pk_fma_f32 v[212:213], v[220:221], v[10:11], v[212:213]
	v_pk_fma_f32 v[214:215], v[222:223], v[12:13], v[214:215]
	s_add_u32 s2, s12, 0x80000
	s_addc_u32 s3, s13, 0
	global_store_dwordx4 v248, v[200:203], s[2:3] offset:64
	s_add_u32 s2, s12, 0x90000
	s_addc_u32 s3, s13, 0
	global_store_dwordx4 v248, v[204:207], s[2:3] offset:64
	s_add_u32 s2, s12, 0xa0000
	s_addc_u32 s3, s13, 0
	global_store_dwordx4 v248, v[208:211], s[2:3] offset:64
	s_add_u32 s2, s12, 0xb0000
	s_addc_u32 s3, s13, 0
	global_store_dwordx4 v248, v[212:215], s[2:3] offset:64
	s_add_u32 s14, s10, 0x80000
	s_addc_u32 s15, s11, 0
	global_load_dwordx4 v[200:203], v248, s[14:15] offset:576 nt
	s_add_u32 s14, s10, 0x90000
	s_addc_u32 s15, s11, 0
	global_load_dwordx4 v[204:207], v248, s[14:15] offset:576 nt
	s_add_u32 s14, s10, 0xa0000
	s_addc_u32 s15, s11, 0
	global_load_dwordx4 v[208:211], v248, s[14:15] offset:576 nt
	s_add_u32 s14, s10, 0xb0000
	s_addc_u32 s15, s11, 0
	global_load_dwordx4 v[212:215], v248, s[14:15] offset:576 nt
	s_waitcnt vmcnt(24)
	v_pk_fma_f32 v[130:131], v[240:241], v[118:119], v[130:131]
	v_pk_fma_f32 v[132:133], v[242:243], v[120:121], v[132:133]
	v_pk_fma_f32 v[134:135], v[240:241], v[102:103], v[134:135]
	v_pk_fma_f32 v[136:137], v[242:243], v[104:105], v[136:137]
	v_pk_fma_f32 v[138:139], v[240:241], v[86:87], v[138:139]
	v_pk_fma_f32 v[140:141], v[242:243], v[88:89], v[140:141]
	v_pk_fma_f32 v[142:143], v[240:241], v[70:71], v[142:143]
	v_pk_fma_f32 v[144:145], v[242:243], v[72:73], v[144:145]
	global_store_dwordx4 v248, v[130:133], s[12:13] offset:512
	s_add_u32 s2, s12, 0x10000
	s_addc_u32 s3, s13, 0
	global_store_dwordx4 v248, v[134:137], s[2:3] offset:512
	s_add_u32 s2, s12, 0x20000
	s_addc_u32 s3, s13, 0
	global_store_dwordx4 v248, v[138:141], s[2:3] offset:512
	s_add_u32 s2, s12, 0x30000
	s_addc_u32 s3, s13, 0
	global_store_dwordx4 v248, v[142:145], s[2:3] offset:512
	s_waitcnt vmcnt(20)
	v_pk_fma_f32 v[146:147], v[240:241], v[54:55], v[146:147]
	v_pk_fma_f32 v[148:149], v[242:243], v[56:57], v[148:149]
	v_pk_fma_f32 v[150:151], v[240:241], v[38:39], v[150:151]
	v_pk_fma_f32 v[152:153], v[242:243], v[40:41], v[152:153]
	v_pk_fma_f32 v[154:155], v[240:241], v[22:23], v[154:155]
	v_pk_fma_f32 v[156:157], v[242:243], v[24:25], v[156:157]
	v_pk_fma_f32 v[158:159], v[240:241], v[6:7], v[158:159]
	v_pk_fma_f32 v[160:161], v[242:243], v[8:9], v[160:161]
	s_add_u32 s2, s12, 0x80000
	s_addc_u32 s3, s13, 0
	global_store_dwordx4 v248, v[146:149], s[2:3] offset:512
	s_add_u32 s2, s12, 0x90000
	s_addc_u32 s3, s13, 0
	global_store_dwordx4 v248, v[150:153], s[2:3] offset:512
	s_add_u32 s2, s12, 0xa0000
	s_addc_u32 s3, s13, 0
	global_store_dwordx4 v248, v[154:157], s[2:3] offset:512
	s_add_u32 s2, s12, 0xb0000
	s_addc_u32 s3, s13, 0
	global_store_dwordx4 v248, v[158:161], s[2:3] offset:512
	s_waitcnt vmcnt(16)
	v_pk_fma_f32 v[162:163], v[244:245], v[114:115], v[162:163]
	v_pk_fma_f32 v[164:165], v[246:247], v[116:117], v[164:165]
	v_pk_fma_f32 v[188:189], v[244:245], v[98:99], v[188:189]
	v_pk_fma_f32 v[190:191], v[246:247], v[100:101], v[190:191]
	v_pk_fma_f32 v[192:193], v[244:245], v[82:83], v[192:193]
	v_pk_fma_f32 v[194:195], v[246:247], v[84:85], v[194:195]
	v_pk_fma_f32 v[196:197], v[244:245], v[66:67], v[196:197]
	v_pk_fma_f32 v[198:199], v[246:247], v[68:69], v[198:199]
	global_store_dwordx4 v248, v[162:165], s[12:13] offset:576
	s_add_u32 s2, s12, 0x10000
	s_addc_u32 s3, s13, 0
	global_store_dwordx4 v248, v[188:191], s[2:3] offset:576
	s_add_u32 s2, s12, 0x20000
	s_addc_u32 s3, s13, 0
	global_store_dwordx4 v248, v[192:195], s[2:3] offset:576
	s_add_u32 s2, s12, 0x30000
	s_addc_u32 s3, s13, 0
	global_store_dwordx4 v248, v[196:199], s[2:3] offset:576
	s_waitcnt vmcnt(12)
	v_pk_fma_f32 v[200:201], v[244:245], v[50:51], v[200:201]
	v_pk_fma_f32 v[202:203], v[246:247], v[52:53], v[202:203]
	v_pk_fma_f32 v[204:205], v[244:245], v[34:35], v[204:205]
	v_pk_fma_f32 v[206:207], v[246:247], v[36:37], v[206:207]
	v_pk_fma_f32 v[208:209], v[244:245], v[18:19], v[208:209]
	v_pk_fma_f32 v[210:211], v[246:247], v[20:21], v[210:211]
	v_pk_fma_f32 v[212:213], v[244:245], v[2:3], v[212:213]
	v_pk_fma_f32 v[214:215], v[246:247], v[4:5], v[214:215]
	s_add_u32 s2, s12, 0x80000
	s_addc_u32 s3, s13, 0
	global_store_dwordx4 v248, v[200:203], s[2:3] offset:576
	s_add_u32 s2, s12, 0x90000
	s_addc_u32 s3, s13, 0
	global_store_dwordx4 v248, v[204:207], s[2:3] offset:576
	s_add_u32 s2, s12, 0xa0000
	s_addc_u32 s3, s13, 0
	global_store_dwordx4 v248, v[208:211], s[2:3] offset:576
	s_add_u32 s2, s12, 0xb0000
	s_addc_u32 s3, s13, 0
	global_store_dwordx4 v248, v[212:215], s[2:3] offset:576
	s_branch .LBB0_561
.Lrf_fused:
	global_load_dwordx4 v[130:133], v248, s[10:11] offset:0 nt
	s_add_u32 s14, s10, 0x10000
	s_addc_u32 s15, s11, 0
	global_load_dwordx4 v[134:137], v248, s[14:15] offset:0 nt
	s_add_u32 s14, s10, 0x20000
	s_addc_u32 s15, s11, 0
	global_load_dwordx4 v[138:141], v248, s[14:15] offset:0 nt
	s_add_u32 s14, s10, 0x30000
	s_addc_u32 s15, s11, 0
	global_load_dwordx4 v[142:145], v248, s[14:15] offset:0 nt
	s_add_u32 s14, s10, 0x80000
	s_addc_u32 s15, s11, 0
	global_load_dwordx4 v[146:149], v248, s[14:15] offset:0 nt
	s_add_u32 s14, s10, 0x90000
	s_addc_u32 s15, s11, 0
	global_load_dwordx4 v[150:153], v248, s[14:15] offset:0 nt
	s_add_u32 s14, s10, 0xa0000
	s_addc_u32 s15, s11, 0
	global_load_dwordx4 v[154:157], v248, s[14:15] offset:0 nt
	s_add_u32 s14, s10, 0xb0000
	s_addc_u32 s15, s11, 0
	global_load_dwordx4 v[158:161], v248, s[14:15] offset:0 nt
	global_load_dwordx4 v[162:165], v248, s[10:11] offset:64 nt
	s_add_u32 s14, s10, 0x10000
	s_addc_u32 s15, s11, 0
	global_load_dwordx4 v[188:191], v248, s[14:15] offset:64 nt
	s_add_u32 s14, s10, 0x20000
	s_addc_u32 s15, s11, 0
	global_load_dwordx4 v[192:195], v248, s[14:15] offset:64 nt
	s_add_u32 s14, s10, 0x30000
	s_addc_u32 s15, s11, 0
	global_load_dwordx4 v[196:199], v248, s[14:15] offset:64 nt
	s_add_u32 s14, s10, 0x80000
	s_addc_u32 s15, s11, 0
	global_load_dwordx4 v[200:203], v248, s[14:15] offset:64 nt
	s_add_u32 s14, s10, 0x90000
	s_addc_u32 s15, s11, 0
	global_load_dwordx4 v[204:207], v248, s[14:15] offset:64 nt
	s_add_u32 s14, s10, 0xa0000
	s_addc_u32 s15, s11, 0
	global_load_dwordx4 v[208:211], v248, s[14:15] offset:64 nt
	s_add_u32 s14, s10, 0xb0000
	s_addc_u32 s15, s11, 0
	global_load_dwordx4 v[212:215], v248, s[14:15] offset:64 nt
	s_waitcnt vmcnt(12)
	v_pk_mul_f32 v[216:217], s[28:29], v[216:217]
	v_pk_mul_f32 v[218:219], s[28:29], v[218:219]
	v_pk_mul_f32 v[220:221], s[28:29], v[220:221]
	v_pk_mul_f32 v[222:223], s[28:29], v[222:223]
	v_pk_mul_f32 v[240:241], s[28:29], v[240:241]
	v_pk_mul_f32 v[242:243], s[28:29], v[242:243]
	v_pk_mul_f32 v[244:245], s[28:29], v[244:245]
	v_pk_mul_f32 v[246:247], s[28:29], v[246:247]
	v_pk_fma_f32 v[126:127], v[216:217], v[126:127], v[130:131]
	v_pk_fma_f32 v[128:129], v[218:219], v[128:129], v[132:133]
	v_pk_fma_f32 v[110:111], v[216:217], v[110:111], v[134:135]
	v_pk_fma_f32 v[112:113], v[218:219], v[112:113], v[136:137]
	v_pk_fma_f32 v[94:95], v[216:217], v[94:95], v[138:139]
	v_pk_fma_f32 v[96:97], v[218:219], v[96:97], v[140:141]
	v_pk_fma_f32 v[78:79], v[216:217], v[78:79], v[142:143]
	v_pk_fma_f32 v[80:81], v[218:219], v[80:81], v[144:145]
	global_load_dwordx4 v[130:133], v248, s[10:11] offset:512 nt
	s_add_u32 s14, s10, 0x10000
	s_addc_u32 s15, s11, 0
	global_load_dwordx4 v[134:137], v248, s[14:15] offset:512 nt
	s_add_u32 s14, s10, 0x20000
	s_addc_u32 s15, s11, 0
	global_load_dwordx4 v[138:141], v248, s[14:15] offset:512 nt
	s_add_u32 s14, s10, 0x30000
	s_addc_u32 s15, s11, 0
	global_load_dwordx4 v[142:145], v248, s[14:15] offset:512 nt
	s_waitcnt vmcnt(12)
	v_pk_fma_f32 v[62:63], v[216:217], v[62:63], v[146:147]
	v_pk_fma_f32 v[64:65], v[218:219], v[64:65], v[148:149]
	v_pk_fma_f32 v[46:47], v[216:217], v[46:47], v[150:151]
	v_pk_fma_f32 v[48:49], v[218:219], v[48:49], v[152:153]
	v_pk_fma_f32 v[30:31], v[216:217], v[30:31], v[154:155]
	v_pk_fma_f32 v[32:33], v[218:219], v[32:33], v[156:157]
	v_pk_fma_f32 v[14:15], v[216:217], v[14:15], v[158:159]
	v_pk_fma_f32 v[16:17], v[218:219], v[16:17], v[160:161]
	s_add_u32 s14, s10, 0x80000
	s_addc_u32 s15, s11, 0
	global_load_dwordx4 v[146:149], v248, s[14:15] offset:512 nt
	s_add_u32 s14, s10, 0x90000
	s_addc_u32 s15, s11, 0
	global_load_dwordx4 v[150:153], v248, s[14:15] offset:512 nt
	s_add_u32 s14, s10, 0xa0000
	s_addc_u32 s15, s11, 0
	global_load_dwordx4 v[154:157], v248, s[14:15] offset:512 nt
	s_add_u32 s14, s10, 0xb0000
	s_addc_u32 s15, s11, 0
	global_load_dwordx4 v[158:161], v248, s[14:15] offset:512 nt
	s_waitcnt vmcnt(12)
	v_pk_fma_f32 v[122:123], v[220:221], v[122:123], v[162:163]
	v_pk_fma_f32 v[124:125], v[222:223], v[124:125], v[164:165]
	v_pk_fma_f32 v[106:107], v[220:221], v[106:107], v[188:189]
	v_pk_fma_f32 v[108:109], v[222:223], v[108:109], v[190:191]
	v_pk_fma_f32 v[90:91], v[220:221], v[90:91], v[192:193]
	v_pk_fma_f32 v[92:93], v[222:223], v[92:93], v[194:195]
	v_pk_fma_f32 v[74:75], v[220:221], v[74:75], v[196:197]
	v_pk_fma_f32 v[76:77], v[222:223], v[76:77], v[198:199]
	global_load_dwordx4 v[162:165], v248, s[10:11] offset:576 nt
	s_add_u32 s14, s10, 0x10000
	s_addc_u32 s15, s11, 0
	global_load_dwordx4 v[188:191], v248, s[14:15] offset:576 nt
	s_add_u32 s14, s10, 0x20000
	s_addc_u32 s15, s11, 0
	global_load_dwordx4 v[192:195], v248, s[14:15] offset:576 nt
	s_add_u32 s14, s10, 0x30000
	s_addc_u32 s15, s11, 0
	global_load_dwordx4 v[196:199], v248, s[14:15] offset:576 nt
	s_waitcnt vmcnt(12)
	v_pk_fma_f32 v[58:59], v[220:221], v[58:59], v[200:201]
	v_pk_fma_f32 v[60:61], v[222:223], v[60:61], v[202:203]
	v_pk_fma_f32 v[42:43], v[220:221], v[42:43], v[204:205]
	v_pk_fma_f32 v[44:45], v[222:223], v[44:45], v[206:207]
	v_pk_fma_f32 v[26:27], v[220:221], v[26:27], v[208:209]
	v_pk_fma_f32 v[28:29], v[222:223], v[28:29], v[210:211]
	v_pk_fma_f32 v[10:11], v[220:221], v[10:11], v[212:213]
	v_pk_fma_f32 v[12:13], v[222:223], v[12:13], v[214:215]
	s_add_u32 s14, s10, 0x80000
	s_addc_u32 s15, s11, 0
	global_load_dwordx4 v[200:203], v248, s[14:15] offset:576 nt
	s_add_u32 s14, s10, 0x90000
	s_addc_u32 s15, s11, 0
	global_load_dwordx4 v[204:207], v248, s[14:15] offset:576 nt
	s_add_u32 s14, s10, 0xa0000
	s_addc_u32 s15, s11, 0
	global_load_dwordx4 v[208:211], v248, s[14:15] offset:576 nt
	s_add_u32 s14, s10, 0xb0000
	s_addc_u32 s15, s11, 0
	global_load_dwordx4 v[212:215], v248, s[14:15] offset:576 nt
	s_waitcnt vmcnt(12)
	v_pk_fma_f32 v[118:119], v[240:241], v[118:119], v[130:131]
	v_pk_fma_f32 v[120:121], v[242:243], v[120:121], v[132:133]
	v_pk_fma_f32 v[102:103], v[240:241], v[102:103], v[134:135]
	v_pk_fma_f32 v[104:105], v[242:243], v[104:105], v[136:137]
	v_pk_fma_f32 v[86:87], v[240:241], v[86:87], v[138:139]
	v_pk_fma_f32 v[88:89], v[242:243], v[88:89], v[140:141]
	v_pk_fma_f32 v[70:71], v[240:241], v[70:71], v[142:143]
	v_pk_fma_f32 v[72:73], v[242:243], v[72:73], v[144:145]
	s_waitcnt vmcnt(8)
	v_pk_fma_f32 v[54:55], v[240:241], v[54:55], v[146:147]
	v_pk_fma_f32 v[56:57], v[242:243], v[56:57], v[148:149]
	v_pk_fma_f32 v[38:39], v[240:241], v[38:39], v[150:151]
	v_pk_fma_f32 v[40:41], v[242:243], v[40:41], v[152:153]
	v_pk_fma_f32 v[22:23], v[240:241], v[22:23], v[154:155]
	v_pk_fma_f32 v[24:25], v[242:243], v[24:25], v[156:157]
	v_pk_fma_f32 v[6:7], v[240:241], v[6:7], v[158:159]
	v_pk_fma_f32 v[8:9], v[242:243], v[8:9], v[160:161]
	s_waitcnt vmcnt(4)
	v_pk_fma_f32 v[114:115], v[244:245], v[114:115], v[162:163]
	v_pk_fma_f32 v[116:117], v[246:247], v[116:117], v[164:165]
	v_pk_fma_f32 v[98:99], v[244:245], v[98:99], v[188:189]
	v_pk_fma_f32 v[100:101], v[246:247], v[100:101], v[190:191]
	v_pk_fma_f32 v[82:83], v[244:245], v[82:83], v[192:193]
	v_pk_fma_f32 v[84:85], v[246:247], v[84:85], v[194:195]
	v_pk_fma_f32 v[66:67], v[244:245], v[66:67], v[196:197]
	v_pk_fma_f32 v[68:69], v[246:247], v[68:69], v[198:199]
	s_waitcnt vmcnt(0)
	v_pk_fma_f32 v[50:51], v[244:245], v[50:51], v[200:201]
	v_pk_fma_f32 v[52:53], v[246:247], v[52:53], v[202:203]
	v_pk_fma_f32 v[34:35], v[244:245], v[34:35], v[204:205]
	v_pk_fma_f32 v[36:37], v[246:247], v[36:37], v[206:207]
	v_pk_fma_f32 v[18:19], v[244:245], v[18:19], v[208:209]
	v_pk_fma_f32 v[20:21], v[246:247], v[20:21], v[210:211]
	v_pk_fma_f32 v[2:3], v[244:245], v[2:3], v[212:213]
	v_pk_fma_f32 v[4:5], v[246:247], v[4:5], v[214:215]
	s_mov_b32 s2, s100
	s_mov_b64 s[100:101], s[12:13]
	s_cmp_eq_u32 s2, 99
	s_cbranch_scc1 .Lrf_finp
	s_ashr_i32 s8, s2, 2
	s_and_b32 s9, s2, 3
	s_mul_i32 s10, s8, 3
	s_add_i32 s11, s10, s9
	s_lshl_b32 s12, s17, 8
	s_sub_i32 s12, s12, 0x1800
	s_max_i32 s12, s12, 0
	s_lshr_b32 s12, s12, 11
	s_add_i32 s10, s10, s12
	s_mul_i32 s10, s10, 0x9000
	s_mul_i32 s9, s9, 0x3000
	s_add_i32 s10, s10, s9
	s_add_i32 s10, s10, 0x100000
	v_readlane_b32 s14, v255, 7
	v_readlane_b32 s15, v255, 8
	s_add_u32 s14, s14, s10
	s_addc_u32 s15, s15, 0
	s_add_u32 s12, s14, 0x1000
	s_addc_u32 s13, s15, 0
	v_readlane_b32 s8, v255, 14
	v_readlane_b32 s9, v255, 15
	s_load_dwordx2 s[8:9], s[8:9], 0x58
	s_lshl_b32 s11, s11, 12
	s_waitcnt lgkmcnt(0)
	s_add_u32 s8, s8, s11
	s_addc_u32 s9, s9, 0
	global_load_dwordx4 v[130:133], v250, s[8:9] offset:0
	global_load_dwordx4 v[146:149], v250, s[12:13] offset:0
	global_load_dwordx4 v[162:165], v250, s[14:15] offset:0
	global_load_dwordx4 v[134:137], v250, s[8:9] offset:64
	global_load_dwordx4 v[150:153], v250, s[12:13] offset:64
	global_load_dwordx4 v[188:191], v250, s[14:15] offset:64
	global_load_dwordx4 v[138:141], v250, s[8:9] offset:512
	global_load_dwordx4 v[154:157], v250, s[12:13] offset:512
	global_load_dwordx4 v[192:195], v250, s[14:15] offset:512
	global_load_dwordx4 v[142:145], v250, s[8:9] offset:576
	global_load_dwordx4 v[158:161], v250, s[12:13] offset:576
	global_load_dwordx4 v[196:199], v250, s[14:15] offset:576
	s_branch .Lrf_pdone
